# de-serialised latency ladders: FIN slab loads, CONV conv-state copy (16 load->store pairs), RMS sample-row gain loads issued together
# speedup vs baseline: 1.0170x; 1.0104x over previous
.LBB0_17:
	v_lshl_add_u64 v[16:17], s[10:11], 0, v[4:5]
	v_lshl_add_u64 v[14:15], s[4:5], 0, v[4:5]
	global_load_dwordx4 v[6:9], v[14:15], off
	v_add_co_u32_e32 v50, vcc, 0x20100000, v16
	s_nop 1
	v_addc_co_u32_e32 v51, vcc, 0, v17, vcc
	global_load_dwordx4 v[18:21], v[50:51], off
	v_add_co_u32_e32 v52, vcc, 0x20900000, v16
	s_nop 1
	v_addc_co_u32_e32 v53, vcc, 0, v17, vcc
	global_load_dwordx4 v[22:25], v[52:53], off
	v_add_co_u32_e32 v54, vcc, 0x21100000, v16
	s_nop 1
	v_addc_co_u32_e32 v55, vcc, 0, v17, vcc
	global_load_dwordx4 v[26:29], v[54:55], off
	v_add_co_u32_e32 v56, vcc, 0x21900000, v16
	s_nop 1
	v_addc_co_u32_e32 v57, vcc, 0, v17, vcc
	global_load_dwordx4 v[30:33], v[56:57], off
	v_add_co_u32_e32 v58, vcc, 0x22100000, v16
	s_nop 1
	v_addc_co_u32_e32 v59, vcc, 0, v17, vcc
	global_load_dwordx4 v[34:37], v[58:59], off
	v_add_co_u32_e32 v60, vcc, 0x22900000, v16
	s_nop 1
	v_addc_co_u32_e32 v61, vcc, 0, v17, vcc
	global_load_dwordx4 v[38:41], v[60:61], off
	v_add_co_u32_e32 v62, vcc, 0x23100000, v16
	s_nop 1
	v_addc_co_u32_e32 v63, vcc, 0, v17, vcc
	global_load_dwordx4 v[42:45], v[62:63], off
	v_add_co_u32_e32 v64, vcc, 0x23900000, v16
	s_nop 1
	v_addc_co_u32_e32 v65, vcc, 0, v17, vcc
	global_load_dwordx4 v[46:49], v[64:65], off
	s_add_u32 s4, s4, s12
	s_addc_u32 s5, s5, s13
	v_add_u32_e32 v2, s92, v2
	s_add_u32 s10, s10, s12
	s_mov_b32 s2, 0x7ffff
	s_addc_u32 s11, s11, s13
	s_waitcnt vmcnt(7)
	v_pk_add_f32 v[10:11], v[6:7], v[18:19]
	v_pk_add_f32 v[12:13], v[8:9], v[20:21]
	s_waitcnt vmcnt(6)
	v_pk_add_f32 v[10:11], v[10:11], v[22:23]
	v_pk_add_f32 v[12:13], v[12:13], v[24:25]
	s_waitcnt vmcnt(5)
	v_pk_add_f32 v[10:11], v[10:11], v[26:27]
	v_pk_add_f32 v[12:13], v[12:13], v[28:29]
	s_waitcnt vmcnt(4)
	v_pk_add_f32 v[10:11], v[10:11], v[30:31]
	v_pk_add_f32 v[12:13], v[12:13], v[32:33]
	s_waitcnt vmcnt(3)
	v_pk_add_f32 v[10:11], v[10:11], v[34:35]
	v_pk_add_f32 v[12:13], v[12:13], v[36:37]
	s_waitcnt vmcnt(2)
	v_pk_add_f32 v[10:11], v[10:11], v[38:39]
	v_pk_add_f32 v[12:13], v[12:13], v[40:41]
	s_waitcnt vmcnt(1)
	v_pk_add_f32 v[10:11], v[10:11], v[42:43]
	v_pk_add_f32 v[12:13], v[12:13], v[44:45]
	s_waitcnt vmcnt(0)
	v_pk_add_f32 v[10:11], v[10:11], v[46:47]
	v_pk_add_f32 v[12:13], v[12:13], v[48:49]
	v_cmp_lt_i32_e32 vcc, s2, v2
	s_or_b64 s[6:7], vcc, s[6:7]
	global_store_dwordx4 v[14:15], v[10:13], off
	s_andn2_b64 exec, exec, s[6:7]
	s_cbranch_execnz .LBB0_17

.LBB0_24:
	s_or_b64 exec, exec, s[4:5]
	s_xor_b64 s[0:1], s[0:1], -1
	v_cndmask_b32_e64 v4, 0, 1, s[0:1]
	v_add_u32_e32 v6, v87, v4
	v_mov_b64_e32 v[4:5], s[14:15]
	s_mov_b32 s0, 0xb000
	v_mad_i64_i32 v[4:5], s[0:1], v6, s0, v[4:5]
	v_lshl_add_u64 v[4:5], v[4:5], 0, v[82:83]
	v_lshl_add_u64 v[2:3], v[2:3], 0, v[82:83]
	v_add_co_u32_e32 v6, vcc, 0x5000, v4
	s_nop 1
	v_addc_co_u32_e32 v7, vcc, 0, v5, vcc
	v_lshl_add_u64 v[8:9], v[4:5], 0, s[48:49]
	v_add_co_u32_e32 v10, vcc, 0x5000, v2
	s_nop 1
	v_addc_co_u32_e32 v11, vcc, 0, v3, vcc
	global_load_dword v12, v[4:5], off
	global_load_dword v13, v[6:7], off offset:2048
	global_load_dword v14, v[4:5], off offset:4
	global_load_dword v15, v[8:9], off offset:4
	global_load_dword v16, v[4:5], off offset:8
	global_load_dword v17, v[8:9], off offset:8
	global_load_dword v18, v[4:5], off offset:12
	global_load_dword v19, v[8:9], off offset:12
	global_load_dword v20, v[4:5], off offset:16
	global_load_dword v21, v[8:9], off offset:16
	global_load_dword v22, v[4:5], off offset:20
	global_load_dword v23, v[8:9], off offset:20
	global_load_dword v24, v[4:5], off offset:24
	global_load_dword v25, v[8:9], off offset:24
	global_load_dword v26, v[4:5], off offset:28
	global_load_dword v27, v[8:9], off offset:28
	s_waitcnt vmcnt(0)
	global_store_dword v[2:3], v12, off
	global_store_dword v[10:11], v13, off offset:2048
	global_store_dword v[2:3], v14, off offset:4
	global_store_dword v[10:11], v15, off offset:2052
	global_store_dword v[2:3], v16, off offset:8
	global_store_dword v[10:11], v17, off offset:2056
	global_store_dword v[2:3], v18, off offset:12
	global_store_dword v[10:11], v19, off offset:2060
	global_store_dword v[2:3], v20, off offset:16
	global_store_dword v[10:11], v21, off offset:2064
	global_store_dword v[2:3], v22, off offset:20
	global_store_dword v[10:11], v23, off offset:2068
	global_store_dword v[2:3], v24, off offset:24
	global_store_dword v[10:11], v25, off offset:2072
	global_store_dword v[2:3], v26, off offset:28
	global_store_dword v[10:11], v27, off offset:2076

.LBB0_48:
	s_cmpk_gt_i32 s4, 0x1fff
	s_mov_b64 s[0:1], -1
	s_cbranch_scc0 .LBB0_50
	s_add_i32 s88, s4, 0xffffe000
	s_lshl_b64 s[2:3], s[88:89], 13
	v_lshl_add_u64 v[146:147], v[126:127], 0, s[2:3]
	v_add_co_u32_e32 v148, vcc, 0x1000, v146
	v_lshl_add_u64 v[150:151], v[128:129], 0, s[2:3]
	s_nop 0
	v_addc_co_u32_e32 v149, vcc, 0, v147, vcc
	v_add_co_u32_e32 v30, vcc, 0x1000, v150
	global_load_dwordx4 v[54:57], v[146:147], off
	global_load_dwordx4 v[26:29], v[146:147], off offset:1024
	global_load_dwordx4 v[18:21], v[146:147], off offset:2048
	global_load_dwordx4 v[10:13], v[146:147], off offset:3072
	v_addc_co_u32_e32 v31, vcc, 0, v151, vcc
	v_add_co_u32_e32 v58, vcc, 0x800000, v150
	global_load_dwordx4 v[22:25], v[148:149], off
	global_load_dwordx4 v[14:17], v[148:149], off offset:1024
	global_load_dwordx4 v[6:9], v[148:149], off offset:2048
	global_load_dwordx4 v[2:5], v[148:149], off offset:3072
	v_addc_co_u32_e32 v59, vcc, 0, v151, vcc
	global_load_dwordx4 v[86:89], v[150:151], off
	global_load_dwordx4 v[66:69], v[150:151], off offset:1024
	global_load_dwordx4 v[46:49], v[150:151], off offset:2048
	global_load_dwordx4 v[38:41], v[150:151], off offset:3072
	global_load_dwordx4 v[50:53], v[30:31], off
	global_load_dwordx4 v[42:45], v[30:31], off offset:1024
	global_load_dwordx4 v[34:37], v[30:31], off offset:2048
	s_nop 0
	global_load_dwordx4 v[30:33], v[30:31], off offset:3072
	s_nop 0
	global_load_dwordx4 v[122:125], v[58:59], off
	global_load_dwordx4 v[98:101], v[58:59], off offset:1024
	global_load_dwordx4 v[82:85], v[58:59], off offset:2048
	global_load_dwordx4 v[74:77], v[58:59], off offset:3072
	v_add_co_u32_e32 v58, vcc, 0x801000, v150
	s_mov_b32 s2, 0x800000
	s_nop 0
	v_addc_co_u32_e32 v59, vcc, 0, v151, vcc
	v_add_co_u32_e32 v90, vcc, 0x1000000, v150
	global_load_dwordx4 v[78:81], v[58:59], off
	global_load_dwordx4 v[70:73], v[58:59], off offset:1024
	global_load_dwordx4 v[62:65], v[58:59], off offset:2048
	s_nop 0
	global_load_dwordx4 v[58:61], v[58:59], off offset:3072
	v_addc_co_u32_e32 v91, vcc, 0, v151, vcc
	global_load_dwordx4 v[152:155], v[90:91], off
	global_load_dwordx4 v[118:121], v[90:91], off offset:1024
	global_load_dwordx4 v[110:113], v[90:91], off offset:2048
	global_load_dwordx4 v[102:105], v[90:91], off offset:3072
	v_add_co_u32_e32 v90, vcc, 0x1001000, v150
	s_mov_b32 s5, s89
	s_nop 0
	v_addc_co_u32_e32 v91, vcc, 0, v151, vcc
	v_add_co_u32_e32 v168, vcc, 0x1800000, v150
	global_load_dwordx4 v[114:117], v[90:91], off
	global_load_dwordx4 v[106:109], v[90:91], off offset:1024
	global_load_dwordx4 v[94:97], v[90:91], off offset:2048
	s_nop 0
	global_load_dwordx4 v[90:93], v[90:91], off offset:3072
	v_addc_co_u32_e32 v169, vcc, 0, v151, vcc
	global_load_dwordx4 v[156:159], v[168:169], off
	global_load_dwordx4 v[160:163], v[168:169], off offset:1024
	global_load_dwordx4 v[164:167], v[168:169], off offset:2048
	global_load_dwordx4 v[180:183], v[168:169], off offset:3072
	v_add_co_u32_e32 v168, vcc, 0x1801000, v150
	s_lshl_b64 s[0:1], s[4:5], 12
	s_nop 0
	v_addc_co_u32_e32 v169, vcc, 0, v151, vcc
	global_load_dwordx4 v[184:187], v[168:169], off
	global_load_dwordx4 v[192:195], v[168:169], off offset:1024
	global_load_dwordx4 v[196:199], v[168:169], off offset:2048
	global_load_dwordx4 v[200:203], v[168:169], off offset:3072
	s_waitcnt vmcnt(23)
	v_pk_add_f32 v[88:89], v[88:89], v[124:125]
	v_pk_add_f32 v[86:87], v[86:87], v[122:123]
	s_waitcnt vmcnt(7)
	v_pk_add_f32 v[122:123], v[154:155], v[158:159]
	v_pk_add_f32 v[124:125], v[152:153], v[156:157]
	v_pk_add_f32 v[88:89], v[88:89], v[122:123]
	v_pk_add_f32 v[86:87], v[86:87], v[124:125]
	v_pk_add_f32 v[124:125], v[56:57], v[88:89]
	v_pk_add_f32 v[122:123], v[54:55], v[86:87]
	v_pk_add_f32 v[54:55], v[68:69], v[100:101]
	v_pk_add_f32 v[56:57], v[66:67], v[98:99]
	s_waitcnt vmcnt(6)
	v_pk_add_f32 v[66:67], v[120:121], v[162:163]
	v_pk_add_f32 v[68:69], v[118:119], v[160:161]
	v_pk_add_f32 v[54:55], v[54:55], v[66:67]
	v_pk_add_f32 v[56:57], v[56:57], v[68:69]
	v_pk_add_f32 v[174:175], v[28:29], v[54:55]
	v_pk_add_f32 v[172:173], v[26:27], v[56:57]
	v_pk_add_f32 v[26:27], v[48:49], v[84:85]
	v_pk_add_f32 v[28:29], v[46:47], v[82:83]
	s_waitcnt vmcnt(5)
	v_pk_add_f32 v[46:47], v[112:113], v[166:167]
	v_pk_add_f32 v[48:49], v[110:111], v[164:165]
	v_pk_add_f32 v[26:27], v[26:27], v[46:47]
	v_pk_add_f32 v[28:29], v[28:29], v[48:49]
	v_pk_add_f32 v[168:169], v[20:21], v[26:27]
	v_pk_add_f32 v[170:171], v[18:19], v[28:29]
	v_pk_add_f32 v[18:19], v[40:41], v[76:77]
	v_pk_add_f32 v[20:21], v[38:39], v[74:75]
	s_waitcnt vmcnt(4)
	v_pk_add_f32 v[26:27], v[104:105], v[182:183]
	v_pk_add_f32 v[28:29], v[102:103], v[180:181]
	v_pk_add_f32 v[18:19], v[18:19], v[26:27]
	v_pk_add_f32 v[20:21], v[20:21], v[28:29]
	v_pk_add_f32 v[164:165], v[12:13], v[18:19]
	v_pk_add_f32 v[166:167], v[10:11], v[20:21]
	v_pk_add_f32 v[10:11], v[52:53], v[80:81]
	v_pk_add_f32 v[12:13], v[50:51], v[78:79]
	s_waitcnt vmcnt(3)
	v_pk_add_f32 v[18:19], v[116:117], v[186:187]
	v_pk_add_f32 v[20:21], v[114:115], v[184:185]
	v_pk_add_f32 v[10:11], v[10:11], v[18:19]
	v_pk_add_f32 v[12:13], v[12:13], v[20:21]
	v_pk_add_f32 v[160:161], v[24:25], v[10:11]
	v_pk_add_f32 v[162:163], v[22:23], v[12:13]
	v_pk_add_f32 v[10:11], v[44:45], v[72:73]
	v_pk_add_f32 v[12:13], v[42:43], v[70:71]
	s_waitcnt vmcnt(2)
	v_pk_add_f32 v[18:19], v[108:109], v[194:195]
	v_pk_add_f32 v[20:21], v[106:107], v[192:193]
	v_pk_add_f32 v[10:11], v[10:11], v[18:19]
	v_pk_add_f32 v[12:13], v[12:13], v[20:21]
	v_pk_add_f32 v[156:157], v[16:17], v[10:11]
	v_pk_add_f32 v[158:159], v[14:15], v[12:13]
	v_pk_add_f32 v[10:11], v[36:37], v[64:65]
	v_pk_add_f32 v[12:13], v[34:35], v[62:63]
	s_waitcnt vmcnt(1)
	v_pk_add_f32 v[14:15], v[96:97], v[198:199]
	v_pk_add_f32 v[16:17], v[94:95], v[196:197]
	v_pk_add_f32 v[10:11], v[10:11], v[14:15]
	v_pk_add_f32 v[12:13], v[12:13], v[16:17]
	v_pk_add_f32 v[152:153], v[8:9], v[10:11]
	v_pk_add_f32 v[154:155], v[6:7], v[12:13]
	v_pk_add_f32 v[8:9], v[30:31], v[58:59]
	s_waitcnt vmcnt(0)
	v_pk_add_f32 v[12:13], v[90:91], v[200:201]
	v_pk_add_f32 v[6:7], v[32:33], v[60:61]
	v_pk_add_f32 v[8:9], v[8:9], v[12:13]
	v_pk_add_f32 v[10:11], v[92:93], v[202:203]
	v_pk_add_f32 v[120:121], v[2:3], v[8:9]
	v_add_co_u32_e32 v2, vcc, s11, v150
	v_pk_add_f32 v[6:7], v[6:7], v[10:11]
	s_nop 0
	v_addc_co_u32_e32 v3, vcc, 0, v151, vcc
	v_pk_add_f32 v[118:119], v[4:5], v[6:7]
	v_add_co_u32_e32 v4, vcc, s12, v150
	s_nop 1
	v_addc_co_u32_e32 v5, vcc, 0, v151, vcc
	v_add_co_u32_e32 v34, vcc, s13, v150
	global_load_dwordx4 v[30:33], v[4:5], off offset:-4096
	global_load_dwordx4 v[26:29], v[2:3], off offset:1024
	global_load_dwordx4 v[22:25], v[2:3], off offset:2048
	global_load_dwordx4 v[18:21], v[2:3], off offset:3072
	global_load_dwordx4 v[14:17], v[4:5], off
	global_load_dwordx4 v[10:13], v[4:5], off offset:1024
	global_load_dwordx4 v[6:9], v[4:5], off offset:2048
	s_nop 0
	global_load_dwordx4 v[2:5], v[4:5], off offset:3072
	v_addc_co_u32_e32 v35, vcc, 0, v151, vcc
	v_add_co_u32_e32 v36, vcc, s14, v150
	s_nop 1
	v_addc_co_u32_e32 v37, vcc, 0, v151, vcc
	v_add_co_u32_e32 v46, vcc, s15, v150
	global_load_dwordx4 v[82:85], v[36:37], off offset:-4096
	global_load_dwordx4 v[74:77], v[34:35], off offset:1024
	global_load_dwordx4 v[66:69], v[34:35], off offset:2048
	global_load_dwordx4 v[58:61], v[34:35], off offset:3072
	global_load_dwordx4 v[50:53], v[36:37], off
	global_load_dwordx4 v[42:45], v[36:37], off offset:1024
	global_load_dwordx4 v[38:41], v[36:37], off offset:2048
	s_nop 0
	global_load_dwordx4 v[34:37], v[36:37], off offset:3072
	v_addc_co_u32_e32 v47, vcc, 0, v151, vcc
	v_add_co_u32_e32 v48, vcc, s18, v150
	s_waitcnt vmcnt(7)
	v_pk_add_f32 v[32:33], v[32:33], v[84:85]
	v_addc_co_u32_e32 v49, vcc, 0, v151, vcc
	v_add_co_u32_e32 v110, vcc, s19, v150
	global_load_dwordx4 v[94:97], v[48:49], off offset:-4096
	global_load_dwordx4 v[90:93], v[46:47], off offset:1024
	global_load_dwordx4 v[86:89], v[46:47], off offset:2048
	global_load_dwordx4 v[78:81], v[46:47], off offset:3072
	global_load_dwordx4 v[70:73], v[48:49], off
	global_load_dwordx4 v[62:65], v[48:49], off offset:1024
	global_load_dwordx4 v[54:57], v[48:49], off offset:2048
	s_nop 0
	global_load_dwordx4 v[46:49], v[48:49], off offset:3072
	v_addc_co_u32_e32 v111, vcc, 0, v151, vcc
	v_add_co_u32_e32 v150, vcc, s20, v150
	v_pk_add_f32 v[30:31], v[30:31], v[82:83]
	s_nop 0
	v_addc_co_u32_e32 v151, vcc, 0, v151, vcc
	global_load_dwordx4 v[98:101], v[150:151], off offset:-4096
	global_load_dwordx4 v[102:105], v[110:111], off offset:1024
	global_load_dwordx4 v[106:109], v[110:111], off offset:2048
	s_nop 0
	global_load_dwordx4 v[110:113], v[110:111], off offset:3072
	s_nop 0
	global_load_dwordx4 v[114:117], v[150:151], off
	global_load_dwordx4 v[180:183], v[150:151], off offset:1024
	global_load_dwordx4 v[184:187], v[150:151], off offset:2048
	global_load_dwordx4 v[192:195], v[150:151], off offset:3072
	s_waitcnt vmcnt(22)
	v_pk_add_f32 v[28:29], v[28:29], v[76:77]
	v_pk_add_f32 v[26:27], v[26:27], v[74:75]
	s_waitcnt vmcnt(16)
	v_pk_add_f32 v[4:5], v[4:5], v[36:37]
	v_pk_add_f32 v[2:3], v[2:3], v[34:35]
	v_pk_add_f32 v[8:9], v[8:9], v[40:41]
	v_pk_add_f32 v[6:7], v[6:7], v[38:39]
	v_pk_add_f32 v[24:25], v[24:25], v[68:69]
	v_pk_add_f32 v[22:23], v[22:23], v[66:67]
	v_pk_add_f32 v[20:21], v[20:21], v[60:61]
	v_pk_add_f32 v[18:19], v[18:19], v[58:59]
	v_pk_add_f32 v[16:17], v[16:17], v[52:53]
	v_pk_add_f32 v[14:15], v[14:15], v[50:51]
	v_pk_add_f32 v[12:13], v[12:13], v[44:45]
	v_pk_add_f32 v[10:11], v[10:11], v[42:43]
	s_waitcnt vmcnt(7)
	v_pk_add_f32 v[84:85], v[94:95], v[98:99]
	s_waitcnt vmcnt(6)
	v_pk_add_f32 v[76:77], v[90:91], v[102:103]
	v_pk_add_f32 v[82:83], v[96:97], v[100:101]
	v_pk_add_f32 v[30:31], v[30:31], v[84:85]
	v_pk_add_f32 v[74:75], v[92:93], v[104:105]
	v_pk_add_f32 v[26:27], v[26:27], v[76:77]
	v_pk_add_f32 v[32:33], v[32:33], v[82:83]
	v_pk_add_f32 v[30:31], v[122:123], v[30:31]
	v_pk_add_f32 v[28:29], v[28:29], v[74:75]
	v_pk_add_f32 v[26:27], v[172:173], v[26:27]
	s_waitcnt vmcnt(0)
	v_pk_add_f32 v[36:37], v[46:47], v[192:193]
	v_pk_add_f32 v[32:33], v[124:125], v[32:33]
	v_pk_add_f32 v[28:29], v[174:175], v[28:29]
	v_pk_add_f32 v[38:39], v[56:57], v[186:187]
	v_pk_add_f32 v[34:35], v[48:49], v[194:195]
	v_pk_add_f32 v[2:3], v[2:3], v[36:37]
	v_mov_b32_e32 v36, v31
	v_mov_b32_e32 v37, v27
	v_pk_add_f32 v[66:67], v[88:89], v[108:109]
	v_pk_add_f32 v[68:69], v[86:87], v[106:107]
	v_pk_add_f32 v[8:9], v[8:9], v[38:39]
	v_pk_add_f32 v[4:5], v[4:5], v[34:35]
	v_mov_b32_e32 v34, v30
	v_mov_b32_e32 v35, v26
	v_pk_mul_f32 v[36:37], v[36:37], v[36:37]
	v_mov_b32_e32 v38, v33
	v_mov_b32_e32 v39, v29
	v_pk_add_f32 v[24:25], v[24:25], v[66:67]
	v_pk_add_f32 v[22:23], v[22:23], v[68:69]
	v_pk_add_f32 v[60:61], v[78:79], v[110:111]
	v_pk_fma_f32 v[34:35], v[34:35], v[34:35], v[36:37]
	v_mov_b32_e32 v36, v32
	v_mov_b32_e32 v37, v28
	v_pk_mul_f32 v[38:39], v[38:39], v[38:39]
	v_pk_add_f32 v[24:25], v[168:169], v[24:25]
	v_pk_add_f32 v[22:23], v[170:171], v[22:23]
	v_pk_add_f32 v[58:59], v[80:81], v[112:113]
	v_pk_add_f32 v[18:19], v[18:19], v[60:61]
	v_pk_fma_f32 v[36:37], v[36:37], v[36:37], v[38:39]
	v_pk_add_f32 v[20:21], v[20:21], v[58:59]
	v_pk_add_f32 v[18:19], v[166:167], v[18:19]
	v_pk_add_f32 v[40:41], v[54:55], v[184:185]
	v_pk_add_f32 v[34:35], v[34:35], v[36:37]
	v_pk_mul_f32 v[36:37], v[24:25], v[24:25]
	v_pk_mul_f32 v[38:39], v[22:23], v[22:23]
	v_pk_add_f32 v[20:21], v[164:165], v[20:21]
	v_pk_add_f32 v[50:51], v[72:73], v[116:117]
	v_pk_add_f32 v[52:53], v[70:71], v[114:115]
	v_pk_add_f32 v[6:7], v[6:7], v[40:41]
	v_pk_mov_b32 v[40:41], v[38:39], v[36:37] op_sel:[1,0]
	v_mov_b32_e32 v39, v37
	v_mul_f32_e32 v0, v18, v18
	v_pk_add_f32 v[16:17], v[16:17], v[50:51]
	v_pk_add_f32 v[14:15], v[14:15], v[52:53]
	v_pk_add_f32 v[36:37], v[40:41], v[38:39]
	v_pk_fma_f32 v[38:39], v[18:19], v[18:19], v[0:1] op_sel_hi:[1,1,0]
	v_mul_f32_e32 v0, v20, v20
	v_pk_add_f32 v[16:17], v[160:161], v[16:17]
	v_pk_add_f32 v[14:15], v[162:163], v[14:15]
	v_pk_add_f32 v[42:43], v[64:65], v[182:183]
	v_pk_add_f32 v[44:45], v[62:63], v[180:181]
	v_pk_add_f32 v[34:35], v[34:35], v[34:35] op_sel_hi:[0,1]
	v_pk_add_f32 v[36:37], v[36:37], v[36:37] op_sel_hi:[0,1]
	v_pk_fma_f32 v[40:41], v[20:21], v[20:21], v[0:1] op_sel_hi:[1,1,0]
	v_pk_add_f32 v[12:13], v[12:13], v[42:43]
	v_pk_add_f32 v[10:11], v[10:11], v[44:45]
	v_mul_f32_e32 v38, v14, v14
	v_mul_f32_e32 v40, v15, v15
	v_mul_f32_e32 v36, v16, v16
	v_mul_f32_e32 v34, v17, v17
	v_pk_add_f32 v[12:13], v[156:157], v[12:13]
	v_pk_add_f32 v[10:11], v[158:159], v[10:11]
	v_pk_add_f32 v[38:39], v[38:39], v[40:41]
	v_pk_add_f32 v[34:35], v[36:37], v[34:35]
	v_pk_add_f32 v[6:7], v[154:155], v[6:7]
	v_pk_add_f32 v[34:35], v[38:39], v[34:35]
	v_pk_mul_f32 v[36:37], v[12:13], v[12:13]
	v_pk_mul_f32 v[38:39], v[10:11], v[10:11]
	v_pk_add_f32 v[8:9], v[152:153], v[8:9]
	v_pk_mov_b32 v[40:41], v[38:39], v[36:37] op_sel:[1,0]
	v_mov_b32_e32 v39, v37
	v_mul_f32_e32 v0, v6, v6
	v_pk_add_f32 v[36:37], v[40:41], v[38:39]
	v_pk_fma_f32 v[38:39], v[6:7], v[6:7], v[0:1] op_sel_hi:[1,1,0]
	v_mul_f32_e32 v0, v8, v8
	v_pk_add_f32 v[4:5], v[118:119], v[4:5]
	v_pk_add_f32 v[2:3], v[120:121], v[2:3]
	v_pk_add_f32 v[34:35], v[34:35], v[34:35] op_sel_hi:[0,1]
	v_pk_add_f32 v[36:37], v[36:37], v[36:37] op_sel_hi:[0,1]
	v_pk_fma_f32 v[40:41], v[8:9], v[8:9], v[0:1] op_sel_hi:[1,1,0]
	v_mul_f32_e32 v38, v2, v2
	v_mul_f32_e32 v40, v3, v3
	v_mul_f32_e32 v36, v4, v4
	v_mul_f32_e32 v34, v5, v5
	global_store_dwordx4 v[146:147], v[30:33], off
	global_store_dwordx4 v[146:147], v[26:29], off offset:1024
	global_store_dwordx4 v[146:147], v[22:25], off offset:2048
	global_store_dwordx4 v[146:147], v[18:21], off offset:3072
	global_store_dwordx4 v[148:149], v[14:17], off
	global_store_dwordx4 v[148:149], v[10:13], off offset:1024
	global_store_dwordx4 v[148:149], v[6:9], off offset:2048
	global_store_dwordx4 v[148:149], v[2:5], off offset:3072
	v_pk_add_f32 v[38:39], v[38:39], v[40:41]
	v_pk_add_f32 v[34:35], v[36:37], v[34:35]
	s_nop 0
	v_pk_add_f32 v[34:35], v[38:39], v[34:35]
	global_load_dwordx4 v[36:39], v[130:131], off
	global_load_dwordx4 v[84:87], v[130:131], off offset:1024
	global_load_dwordx4 v[88:91], v[130:131], off offset:2048
	global_load_dwordx4 v[92:95], v[130:131], off offset:3072
	global_load_dwordx4 v[96:99], v[134:135], off
	global_load_dwordx4 v[100:103], v[136:137], off
	global_load_dwordx4 v[104:107], v[138:139], off
	global_load_dwordx4 v[108:111], v[140:141], off
	v_add_f32_e32 v0, v34, v35
	v_and_b32_e32 v34, 64, v191
	v_add_u32_e32 v34, 64, v34
	v_xor_b32_e32 v35, 1, v191
	v_cmp_lt_i32_e32 vcc, v35, v34
	s_nop 1
	v_cndmask_b32_e32 v35, v191, v35, vcc
	v_lshlrev_b32_e32 v35, 2, v35
	ds_bpermute_b32 v35, v35, v0
	s_waitcnt lgkmcnt(0)
	v_add_f32_e32 v0, v0, v35
	v_xor_b32_e32 v35, 2, v191
	v_cmp_lt_i32_e32 vcc, v35, v34
	s_nop 1
	v_cndmask_b32_e32 v35, v191, v35, vcc
	v_lshlrev_b32_e32 v35, 2, v35
	ds_bpermute_b32 v35, v35, v0
	s_waitcnt lgkmcnt(0)
	v_add_f32_e32 v0, v0, v35
	v_xor_b32_e32 v35, 4, v191
	v_cmp_lt_i32_e32 vcc, v35, v34
	s_nop 1
	v_cndmask_b32_e32 v35, v191, v35, vcc
	v_lshlrev_b32_e32 v35, 2, v35
	ds_bpermute_b32 v35, v35, v0
	s_waitcnt lgkmcnt(0)
	v_add_f32_e32 v0, v0, v35
	v_xor_b32_e32 v35, 8, v191
	v_cmp_lt_i32_e32 vcc, v35, v34
	s_nop 1
	v_cndmask_b32_e32 v35, v191, v35, vcc
	v_lshlrev_b32_e32 v35, 2, v35
	ds_bpermute_b32 v35, v35, v0
	s_waitcnt lgkmcnt(0)
	v_add_f32_e32 v0, v0, v35
	v_xor_b32_e32 v35, 16, v191
	v_cmp_lt_i32_e32 vcc, v35, v34
	s_nop 1
	v_cndmask_b32_e32 v35, v191, v35, vcc
	v_lshlrev_b32_e32 v35, 2, v35
	ds_bpermute_b32 v35, v35, v0
	s_waitcnt lgkmcnt(0)
	v_add_f32_e32 v0, v0, v35
	v_xor_b32_e32 v35, 32, v191
	v_cmp_lt_i32_e32 vcc, v35, v34
	s_nop 1
	v_cndmask_b32_e32 v34, v191, v35, vcc
	v_lshlrev_b32_e32 v34, 2, v34
	ds_bpermute_b32 v34, v34, v0
	s_waitcnt lgkmcnt(0)
	v_add_f32_e32 v0, v0, v34
	v_fmamk_f32 v0, v0, 0x3a000000, v178
	v_cmp_gt_f32_e32 vcc, s2, v0
	v_mul_f32_e32 v34, 0x4b800000, v0
	s_nop 0
	v_cndmask_b32_e32 v0, v0, v34, vcc
	v_rsq_f32_e32 v0, v0
	s_nop 0
	v_mul_f32_e32 v34, 0x45800000, v0
	v_cndmask_b32_e32 v0, v0, v34, vcc
	v_pk_mul_f32 v[30:31], v[30:31], v[0:1] op_sel_hi:[1,0]
	v_pk_mul_f32 v[32:33], v[32:33], v[0:1] op_sel_hi:[1,0]
	s_waitcnt vmcnt(0)
	v_pk_mul_f32 v[30:31], v[36:37], v[30:31]
	v_pk_mul_f32 v[32:33], v[38:39], v[32:33]
	v_lshl_add_u64 v[34:35], v[132:133], 0, s[0:1]
	v_cvt_pk_bf16_f32 v30, v30, v31
	v_cvt_pk_bf16_f32 v31, v32, v33
	global_store_dwordx2 v[34:35], v[30:31], off
	v_pk_mul_f32 v[26:27], v[26:27], v[0:1] op_sel_hi:[1,0]
	v_pk_mul_f32 v[28:29], v[28:29], v[0:1] op_sel_hi:[1,0]
	v_pk_mul_f32 v[22:23], v[22:23], v[0:1] op_sel_hi:[1,0]
	v_pk_mul_f32 v[24:25], v[24:25], v[0:1] op_sel_hi:[1,0]
	v_pk_mul_f32 v[18:19], v[18:19], v[0:1] op_sel_hi:[1,0]
	v_pk_mul_f32 v[20:21], v[20:21], v[0:1] op_sel_hi:[1,0]
	v_pk_mul_f32 v[14:15], v[14:15], v[0:1] op_sel_hi:[1,0]
	v_pk_mul_f32 v[16:17], v[16:17], v[0:1] op_sel_hi:[1,0]
	v_pk_mul_f32 v[10:11], v[10:11], v[0:1] op_sel_hi:[1,0]
	v_pk_mul_f32 v[12:13], v[12:13], v[0:1] op_sel_hi:[1,0]
	v_pk_mul_f32 v[6:7], v[6:7], v[0:1] op_sel_hi:[1,0]
	v_pk_mul_f32 v[8:9], v[8:9], v[0:1] op_sel_hi:[1,0]
	v_pk_mul_f32 v[2:3], v[2:3], v[0:1] op_sel_hi:[1,0]
	s_mov_b64 s[0:1], 0
	v_pk_mul_f32 v[26:27], v[84:85], v[26:27]
	v_pk_mul_f32 v[28:29], v[86:87], v[28:29]
	v_cvt_pk_bf16_f32 v26, v26, v27
	v_cvt_pk_bf16_f32 v27, v28, v29
	global_store_dwordx2 v[34:35], v[26:27], off offset:512
	v_pk_mul_f32 v[22:23], v[88:89], v[22:23]
	v_pk_mul_f32 v[24:25], v[90:91], v[24:25]
	v_cvt_pk_bf16_f32 v22, v22, v23
	v_cvt_pk_bf16_f32 v23, v24, v25
	global_store_dwordx2 v[34:35], v[22:23], off offset:1024
	v_pk_mul_f32 v[18:19], v[92:93], v[18:19]
	v_pk_mul_f32 v[20:21], v[94:95], v[20:21]
	v_cvt_pk_bf16_f32 v18, v18, v19
	v_cvt_pk_bf16_f32 v19, v20, v21
	global_store_dwordx2 v[34:35], v[18:19], off offset:1536
	v_pk_mul_f32 v[14:15], v[96:97], v[14:15]
	v_pk_mul_f32 v[16:17], v[98:99], v[16:17]
	v_cvt_pk_bf16_f32 v14, v14, v15
	v_cvt_pk_bf16_f32 v15, v16, v17
	global_store_dwordx2 v[34:35], v[14:15], off offset:2048
	v_pk_mul_f32 v[10:11], v[10:11], v[100:101]
	v_pk_mul_f32 v[12:13], v[12:13], v[102:103]
	v_cvt_pk_bf16_f32 v10, v10, v11
	v_cvt_pk_bf16_f32 v11, v12, v13
	global_store_dwordx2 v[34:35], v[10:11], off offset:2560
	v_pk_mul_f32 v[6:7], v[6:7], v[104:105]
	v_pk_mul_f32 v[8:9], v[8:9], v[106:107]
	v_cvt_pk_bf16_f32 v6, v6, v7
	v_cvt_pk_bf16_f32 v7, v8, v9
	global_store_dwordx2 v[34:35], v[6:7], off offset:3072
	s_nop 1
	v_mov_b32_e32 v6, v108
	v_mov_b32_e32 v7, v109
	v_mov_b32_e32 v8, v110
	v_mov_b32_e32 v9, v111
	v_pk_mul_f32 v[2:3], v[2:3], v[6:7]
	v_mul_f32_e32 v6, v4, v0
	v_mov_b32_e32 v4, v8
	v_mov_b32_e32 v7, v0
	v_cvt_pk_bf16_f32 v2, v2, v3
	v_pk_mul_f32 v[4:5], v[4:5], v[6:7]

.LBB0_171:
	s_or_b64 exec, exec, s[4:5]
	s_xor_b64 s[0:1], s[0:1], -1
	v_cndmask_b32_e64 v4, 0, 1, s[0:1]
	v_add_u32_e32 v6, v87, v4
	v_mov_b64_e32 v[4:5], s[14:15]
	s_mov_b32 s0, 0xb000
	v_mad_i64_i32 v[4:5], s[0:1], v6, s0, v[4:5]
	v_lshl_add_u64 v[4:5], v[4:5], 0, v[82:83]
	v_lshl_add_u64 v[2:3], v[2:3], 0, v[82:83]
	v_add_co_u32_e32 v6, vcc, 0x5000, v4
	s_nop 1
	v_addc_co_u32_e32 v7, vcc, 0, v5, vcc
	v_lshl_add_u64 v[8:9], v[4:5], 0, s[40:41]
	v_add_co_u32_e32 v10, vcc, 0x5000, v2
	s_nop 1
	v_addc_co_u32_e32 v11, vcc, 0, v3, vcc
	global_load_dword v12, v[4:5], off
	global_load_dword v13, v[6:7], off offset:2048
	global_load_dword v14, v[4:5], off offset:4
	global_load_dword v15, v[8:9], off offset:4
	global_load_dword v16, v[4:5], off offset:8
	global_load_dword v17, v[8:9], off offset:8
	global_load_dword v18, v[4:5], off offset:12
	global_load_dword v19, v[8:9], off offset:12
	global_load_dword v20, v[4:5], off offset:16
	global_load_dword v21, v[8:9], off offset:16
	global_load_dword v22, v[4:5], off offset:20
	global_load_dword v23, v[8:9], off offset:20
	global_load_dword v24, v[4:5], off offset:24
	global_load_dword v25, v[8:9], off offset:24
	global_load_dword v26, v[4:5], off offset:28
	global_load_dword v27, v[8:9], off offset:28
	s_waitcnt vmcnt(0)
	global_store_dword v[2:3], v12, off
	global_store_dword v[10:11], v13, off offset:2048
	global_store_dword v[2:3], v14, off offset:4
	global_store_dword v[10:11], v15, off offset:2052
	global_store_dword v[2:3], v16, off offset:8
	global_store_dword v[10:11], v17, off offset:2056
	global_store_dword v[2:3], v18, off offset:12
	global_store_dword v[10:11], v19, off offset:2060
	global_store_dword v[2:3], v20, off offset:16
	global_store_dword v[10:11], v21, off offset:2064
	global_store_dword v[2:3], v22, off offset:20
	global_store_dword v[10:11], v23, off offset:2068
	global_store_dword v[2:3], v24, off offset:24
	global_store_dword v[10:11], v25, off offset:2072
	global_store_dword v[2:3], v26, off offset:28
	global_store_dword v[10:11], v27, off offset:2076

.LBB0_682:
	s_cmpk_gt_i32 s4, 0x1fff
	s_mov_b64 s[0:1], -1
	s_cbranch_scc0 .LBB0_684
	s_add_i32 s88, s4, 0xffffe000
	s_lshl_b64 s[6:7], s[88:89], 13
	v_lshl_add_u64 v[2:3], v[122:123], 0, s[6:7]
	global_load_dwordx4 v[58:61], v[2:3], off
	global_load_dwordx4 v[26:29], v[2:3], off offset:1024
	global_load_dwordx4 v[18:21], v[2:3], off offset:2048
	global_load_dwordx4 v[10:13], v[2:3], off offset:3072
	v_add_co_u32_e32 v2, vcc, 0x1000, v2
	v_lshl_add_u64 v[144:145], v[124:125], 0, s[6:7]
	s_nop 0
	v_addc_co_u32_e32 v3, vcc, 0, v3, vcc
	v_add_co_u32_e32 v30, vcc, 0x1000, v144
	global_load_dwordx4 v[22:25], v[2:3], off
	global_load_dwordx4 v[14:17], v[2:3], off offset:1024
	global_load_dwordx4 v[6:9], v[2:3], off offset:2048
	s_nop 0
	global_load_dwordx4 v[2:5], v[2:3], off offset:3072
	v_addc_co_u32_e32 v31, vcc, 0, v145, vcc
	v_add_co_u32_e32 v54, vcc, 0x800000, v144
	global_load_dwordx4 v[102:105], v[144:145], off
	global_load_dwordx4 v[78:81], v[144:145], off offset:1024
	global_load_dwordx4 v[46:49], v[144:145], off offset:2048
	global_load_dwordx4 v[38:41], v[144:145], off offset:3072
	v_addc_co_u32_e32 v55, vcc, 0, v145, vcc
	global_load_dwordx4 v[50:53], v[30:31], off
	global_load_dwordx4 v[42:45], v[30:31], off offset:1024
	global_load_dwordx4 v[34:37], v[30:31], off offset:2048
	s_nop 0
	global_load_dwordx4 v[30:33], v[30:31], off offset:3072
	s_nop 0
	global_load_dwordx4 v[146:149], v[54:55], off
	global_load_dwordx4 v[114:117], v[54:55], off offset:1024
	global_load_dwordx4 v[82:85], v[54:55], off offset:2048
	global_load_dwordx4 v[70:73], v[54:55], off offset:3072
	v_add_co_u32_e32 v54, vcc, 0x801000, v144
	s_movk_i32 s2, 0x1000
	s_nop 0
	v_addc_co_u32_e32 v55, vcc, 0, v145, vcc
	v_add_co_u32_e32 v86, vcc, 0x1000000, v144
	global_load_dwordx4 v[74:77], v[54:55], off
	global_load_dwordx4 v[66:69], v[54:55], off offset:1024
	global_load_dwordx4 v[62:65], v[54:55], off offset:2048
	s_nop 0
	global_load_dwordx4 v[54:57], v[54:55], off offset:3072
	v_addc_co_u32_e32 v87, vcc, 0, v145, vcc
	global_load_dwordx4 v[150:153], v[86:87], off
	global_load_dwordx4 v[118:121], v[86:87], off offset:1024
	global_load_dwordx4 v[106:109], v[86:87], off offset:2048
	global_load_dwordx4 v[94:97], v[86:87], off offset:3072
	v_add_co_u32_e32 v86, vcc, 0x1001000, v144
	s_mov_b32 s5, s89
	s_nop 0
	v_addc_co_u32_e32 v87, vcc, 0, v145, vcc
	v_add_co_u32_e32 v166, vcc, 0x1800000, v144
	global_load_dwordx4 v[110:113], v[86:87], off
	global_load_dwordx4 v[98:101], v[86:87], off offset:1024
	global_load_dwordx4 v[90:93], v[86:87], off offset:2048
	s_nop 0
	global_load_dwordx4 v[86:89], v[86:87], off offset:3072
	v_addc_co_u32_e32 v167, vcc, 0, v145, vcc
	global_load_dwordx4 v[154:157], v[166:167], off
	global_load_dwordx4 v[158:161], v[166:167], off offset:1024
	global_load_dwordx4 v[162:165], v[166:167], off offset:2048
	s_nop 0
	global_load_dwordx4 v[166:169], v[166:167], off offset:3072
	v_add_co_u32_e32 v184, vcc, 0x1801000, v144
	s_lshl_b64 s[0:1], s[4:5], 12
	s_nop 0
	v_addc_co_u32_e32 v185, vcc, 0, v145, vcc
	global_load_dwordx4 v[170:173], v[184:185], off
	global_load_dwordx4 v[174:177], v[184:185], off offset:1024
	global_load_dwordx4 v[180:183], v[184:185], off offset:2048
	s_nop 0
	global_load_dwordx4 v[184:187], v[184:185], off offset:3072
	s_waitcnt vmcnt(23)
	v_pk_add_f32 v[104:105], v[104:105], v[148:149]
	v_pk_add_f32 v[102:103], v[102:103], v[146:147]
	s_waitcnt vmcnt(7)
	v_pk_add_f32 v[146:147], v[152:153], v[156:157]
	v_pk_add_f32 v[148:149], v[150:151], v[154:155]
	v_pk_add_f32 v[104:105], v[104:105], v[146:147]
	v_pk_add_f32 v[102:103], v[102:103], v[148:149]
	v_pk_add_f32 v[146:147], v[60:61], v[104:105]
	v_pk_add_f32 v[148:149], v[58:59], v[102:103]
	v_pk_add_f32 v[58:59], v[80:81], v[116:117]
	v_pk_add_f32 v[60:61], v[78:79], v[114:115]
	s_waitcnt vmcnt(6)
	v_pk_add_f32 v[78:79], v[120:121], v[160:161]
	v_pk_add_f32 v[80:81], v[118:119], v[158:159]
	v_pk_add_f32 v[58:59], v[58:59], v[78:79]
	v_pk_add_f32 v[60:61], v[60:61], v[80:81]
	v_pk_add_f32 v[160:161], v[28:29], v[58:59]
	v_pk_add_f32 v[158:159], v[26:27], v[60:61]
	v_pk_add_f32 v[26:27], v[48:49], v[84:85]
	v_pk_add_f32 v[28:29], v[46:47], v[82:83]
	s_waitcnt vmcnt(5)
	v_pk_add_f32 v[46:47], v[108:109], v[164:165]
	v_pk_add_f32 v[48:49], v[106:107], v[162:163]
	v_pk_add_f32 v[26:27], v[26:27], v[46:47]
	v_pk_add_f32 v[28:29], v[28:29], v[48:49]
	v_pk_add_f32 v[154:155], v[20:21], v[26:27]
	v_pk_add_f32 v[156:157], v[18:19], v[28:29]
	v_pk_add_f32 v[18:19], v[40:41], v[72:73]
	v_pk_add_f32 v[20:21], v[38:39], v[70:71]
	s_waitcnt vmcnt(4)
	v_pk_add_f32 v[26:27], v[96:97], v[168:169]
	v_pk_add_f32 v[28:29], v[94:95], v[166:167]
	v_pk_add_f32 v[18:19], v[18:19], v[26:27]
	v_pk_add_f32 v[20:21], v[20:21], v[28:29]
	v_pk_add_f32 v[150:151], v[12:13], v[18:19]
	v_pk_add_f32 v[152:153], v[10:11], v[20:21]
	v_pk_add_f32 v[10:11], v[52:53], v[76:77]
	v_pk_add_f32 v[12:13], v[50:51], v[74:75]
	s_waitcnt vmcnt(3)
	v_pk_add_f32 v[18:19], v[112:113], v[172:173]
	v_pk_add_f32 v[20:21], v[110:111], v[170:171]
	v_pk_add_f32 v[10:11], v[10:11], v[18:19]
	v_pk_add_f32 v[12:13], v[12:13], v[20:21]
	v_pk_add_f32 v[118:119], v[24:25], v[10:11]
	v_pk_add_f32 v[120:121], v[22:23], v[12:13]
	v_pk_add_f32 v[10:11], v[44:45], v[68:69]
	v_pk_add_f32 v[12:13], v[42:43], v[66:67]
	s_waitcnt vmcnt(2)
	v_pk_add_f32 v[18:19], v[100:101], v[176:177]
	v_pk_add_f32 v[20:21], v[98:99], v[174:175]
	v_pk_add_f32 v[10:11], v[10:11], v[18:19]
	v_pk_add_f32 v[12:13], v[12:13], v[20:21]
	v_pk_add_f32 v[114:115], v[16:17], v[10:11]
	v_pk_add_f32 v[116:117], v[14:15], v[12:13]
	v_pk_add_f32 v[10:11], v[36:37], v[64:65]
	v_pk_add_f32 v[12:13], v[34:35], v[62:63]
	s_waitcnt vmcnt(1)
	v_pk_add_f32 v[14:15], v[92:93], v[182:183]
	v_pk_add_f32 v[16:17], v[90:91], v[180:181]
	v_pk_add_f32 v[10:11], v[10:11], v[14:15]
	v_pk_add_f32 v[12:13], v[12:13], v[16:17]
	v_pk_add_f32 v[110:111], v[8:9], v[10:11]
	v_pk_add_f32 v[112:113], v[6:7], v[12:13]
	v_pk_add_f32 v[8:9], v[30:31], v[54:55]
	s_waitcnt vmcnt(0)
	v_pk_add_f32 v[12:13], v[86:87], v[184:185]
	v_pk_add_f32 v[6:7], v[32:33], v[56:57]
	v_pk_add_f32 v[8:9], v[8:9], v[12:13]
	v_pk_add_f32 v[10:11], v[88:89], v[186:187]
	v_pk_add_f32 v[108:109], v[2:3], v[8:9]
	v_add_co_u32_e32 v2, vcc, s13, v144
	v_pk_add_f32 v[6:7], v[6:7], v[10:11]
	s_nop 0
	v_addc_co_u32_e32 v3, vcc, 0, v145, vcc
	v_pk_add_f32 v[106:107], v[4:5], v[6:7]
	v_add_co_u32_e32 v4, vcc, s14, v144
	s_nop 1
	v_addc_co_u32_e32 v5, vcc, 0, v145, vcc
	v_add_co_u32_e32 v34, vcc, s15, v144
	global_load_dwordx4 v[30:33], v[4:5], off offset:-4096
	global_load_dwordx4 v[26:29], v[2:3], off offset:1024
	global_load_dwordx4 v[22:25], v[2:3], off offset:2048
	global_load_dwordx4 v[18:21], v[2:3], off offset:3072
	global_load_dwordx4 v[14:17], v[4:5], off
	global_load_dwordx4 v[10:13], v[4:5], off offset:1024
	global_load_dwordx4 v[6:9], v[4:5], off offset:2048
	s_nop 0
	global_load_dwordx4 v[2:5], v[4:5], off offset:3072
	v_addc_co_u32_e32 v35, vcc, 0, v145, vcc
	v_add_co_u32_e32 v36, vcc, s18, v144
	s_nop 1
	v_addc_co_u32_e32 v37, vcc, 0, v145, vcc
	v_add_co_u32_e32 v46, vcc, s19, v144
	global_load_dwordx4 v[86:89], v[36:37], off offset:-4096
	global_load_dwordx4 v[78:81], v[34:35], off offset:1024
	global_load_dwordx4 v[66:69], v[34:35], off offset:2048
	global_load_dwordx4 v[58:61], v[34:35], off offset:3072
	global_load_dwordx4 v[50:53], v[36:37], off
	global_load_dwordx4 v[42:45], v[36:37], off offset:1024
	global_load_dwordx4 v[38:41], v[36:37], off offset:2048
	s_nop 0
	global_load_dwordx4 v[34:37], v[36:37], off offset:3072
	v_addc_co_u32_e32 v47, vcc, 0, v145, vcc
	v_add_co_u32_e32 v48, vcc, s20, v144
	s_waitcnt vmcnt(7)
	v_pk_add_f32 v[32:33], v[32:33], v[88:89]
	v_addc_co_u32_e32 v49, vcc, 0, v145, vcc
	v_add_co_u32_e32 v166, vcc, s21, v144
	global_load_dwordx4 v[94:97], v[48:49], off offset:-4096
	global_load_dwordx4 v[90:93], v[46:47], off offset:1024
	global_load_dwordx4 v[82:85], v[46:47], off offset:2048
	global_load_dwordx4 v[74:77], v[46:47], off offset:3072
	global_load_dwordx4 v[70:73], v[48:49], off
	global_load_dwordx4 v[62:65], v[48:49], off offset:1024
	global_load_dwordx4 v[54:57], v[48:49], off offset:2048
	s_nop 0
	global_load_dwordx4 v[46:49], v[48:49], off offset:3072
	v_addc_co_u32_e32 v167, vcc, 0, v145, vcc
	v_add_co_u32_e32 v144, vcc, s22, v144
	v_pk_add_f32 v[30:31], v[30:31], v[86:87]
	s_nop 0
	v_addc_co_u32_e32 v145, vcc, 0, v145, vcc
	global_load_dwordx4 v[98:101], v[144:145], off offset:-4096
	global_load_dwordx4 v[102:105], v[166:167], off offset:1024
	global_load_dwordx4 v[162:165], v[166:167], off offset:2048
	s_nop 0
	global_load_dwordx4 v[166:169], v[166:167], off offset:3072
	s_nop 0
	global_load_dwordx4 v[170:173], v[144:145], off
	global_load_dwordx4 v[174:177], v[144:145], off offset:1024
	global_load_dwordx4 v[180:183], v[144:145], off offset:2048
	global_load_dwordx4 v[184:187], v[144:145], off offset:3072
	s_waitcnt vmcnt(22)
	v_pk_add_f32 v[28:29], v[28:29], v[80:81]
	v_pk_add_f32 v[26:27], v[26:27], v[78:79]
	s_waitcnt vmcnt(21)
	v_pk_add_f32 v[24:25], v[24:25], v[68:69]
	v_pk_add_f32 v[22:23], v[22:23], v[66:67]
	s_waitcnt vmcnt(20)
	v_pk_add_f32 v[20:21], v[20:21], v[60:61]
	v_pk_add_f32 v[18:19], v[18:19], v[58:59]
	s_waitcnt vmcnt(16)
	v_pk_add_f32 v[4:5], v[4:5], v[36:37]
	v_pk_add_f32 v[2:3], v[2:3], v[34:35]
	v_pk_add_f32 v[16:17], v[16:17], v[52:53]
	v_pk_add_f32 v[14:15], v[14:15], v[50:51]
	v_pk_add_f32 v[12:13], v[12:13], v[44:45]
	v_pk_add_f32 v[10:11], v[10:11], v[42:43]
	v_pk_add_f32 v[8:9], v[8:9], v[40:41]
	v_pk_add_f32 v[6:7], v[6:7], v[38:39]
	s_waitcnt vmcnt(7)
	v_pk_add_f32 v[86:87], v[96:97], v[100:101]
	v_pk_add_f32 v[88:89], v[94:95], v[98:99]
	v_pk_add_f32 v[32:33], v[32:33], v[86:87]
	v_pk_add_f32 v[30:31], v[30:31], v[88:89]
	s_waitcnt vmcnt(6)
	v_pk_add_f32 v[78:79], v[92:93], v[104:105]
	v_pk_add_f32 v[80:81], v[90:91], v[102:103]
	s_waitcnt vmcnt(5)
	v_pk_add_f32 v[66:67], v[84:85], v[164:165]
	v_pk_add_f32 v[68:69], v[82:83], v[162:163]
	s_waitcnt vmcnt(4)
	v_pk_add_f32 v[58:59], v[76:77], v[168:169]
	v_pk_add_f32 v[60:61], v[74:75], v[166:167]
	s_waitcnt vmcnt(0)
	v_pk_add_f32 v[34:35], v[48:49], v[186:187]
	v_pk_add_f32 v[32:33], v[146:147], v[32:33]
	v_pk_add_f32 v[30:31], v[148:149], v[30:31]
	v_pk_add_f32 v[28:29], v[28:29], v[78:79]
	v_pk_add_f32 v[26:27], v[26:27], v[80:81]
	v_pk_add_f32 v[24:25], v[24:25], v[66:67]
	v_pk_add_f32 v[22:23], v[22:23], v[68:69]
	v_pk_add_f32 v[20:21], v[20:21], v[58:59]
	v_pk_add_f32 v[18:19], v[18:19], v[60:61]
	v_pk_add_f32 v[50:51], v[72:73], v[172:173]
	v_pk_add_f32 v[52:53], v[70:71], v[170:171]
	v_pk_add_f32 v[4:5], v[4:5], v[34:35]
	v_lshl_add_u64 v[34:35], v[126:127], 0, s[6:7]
	v_pk_add_f32 v[28:29], v[160:161], v[28:29]
	v_pk_add_f32 v[26:27], v[158:159], v[26:27]
	v_pk_add_f32 v[24:25], v[154:155], v[24:25]
	v_pk_add_f32 v[22:23], v[156:157], v[22:23]
	v_pk_add_f32 v[20:21], v[150:151], v[20:21]
	v_pk_add_f32 v[18:19], v[152:153], v[18:19]
	v_pk_add_f32 v[16:17], v[16:17], v[50:51]
	v_pk_add_f32 v[14:15], v[14:15], v[52:53]
	v_pk_add_f32 v[42:43], v[64:65], v[176:177]
	v_pk_add_f32 v[44:45], v[62:63], v[174:175]
	v_pk_add_f32 v[38:39], v[56:57], v[182:183]
	v_pk_add_f32 v[40:41], v[54:55], v[180:181]
	v_pk_add_f32 v[36:37], v[46:47], v[184:185]
	global_store_dwordx4 v[34:35], v[30:33], off
	global_store_dwordx4 v[34:35], v[26:29], off offset:1024
	global_store_dwordx4 v[34:35], v[22:25], off offset:2048
	global_store_dwordx4 v[34:35], v[18:21], off offset:3072
	v_add_co_u32_e32 v34, vcc, s2, v34
	v_pk_add_f32 v[16:17], v[118:119], v[16:17]
	v_pk_add_f32 v[14:15], v[120:121], v[14:15]
	v_pk_add_f32 v[12:13], v[12:13], v[42:43]
	v_pk_add_f32 v[10:11], v[10:11], v[44:45]
	v_pk_add_f32 v[8:9], v[8:9], v[38:39]
	v_pk_add_f32 v[6:7], v[6:7], v[40:41]
	v_pk_add_f32 v[2:3], v[2:3], v[36:37]
	v_addc_co_u32_e32 v35, vcc, 0, v35, vcc
	v_mov_b32_e32 v36, v31
	v_mov_b32_e32 v37, v27
	v_pk_add_f32 v[12:13], v[114:115], v[12:13]
	v_pk_add_f32 v[10:11], v[116:117], v[10:11]
	v_pk_add_f32 v[8:9], v[110:111], v[8:9]
	v_pk_add_f32 v[6:7], v[112:113], v[6:7]
	v_pk_add_f32 v[4:5], v[106:107], v[4:5]
	v_pk_add_f32 v[2:3], v[108:109], v[2:3]
	global_store_dwordx4 v[34:35], v[14:17], off
	global_store_dwordx4 v[34:35], v[10:13], off offset:1024
	global_store_dwordx4 v[34:35], v[6:9], off offset:2048
	global_store_dwordx4 v[34:35], v[2:5], off offset:3072
	v_mov_b32_e32 v34, v30
	v_mov_b32_e32 v35, v26
	v_pk_mul_f32 v[36:37], v[36:37], v[36:37]
	v_mov_b32_e32 v38, v33
	v_mov_b32_e32 v39, v29
	v_pk_fma_f32 v[34:35], v[34:35], v[34:35], v[36:37]
	v_mov_b32_e32 v36, v32
	v_mov_b32_e32 v37, v28
	v_pk_mul_f32 v[38:39], v[38:39], v[38:39]
	v_mul_f32_e32 v0, v18, v18
	v_pk_fma_f32 v[36:37], v[36:37], v[36:37], v[38:39]
	v_pk_mul_f32 v[38:39], v[22:23], v[22:23]
	v_pk_add_f32 v[34:35], v[34:35], v[36:37]
	v_pk_mul_f32 v[36:37], v[24:25], v[24:25]
	v_pk_add_f32 v[34:35], v[34:35], v[34:35] op_sel_hi:[0,1]
	v_pk_mov_b32 v[40:41], v[38:39], v[36:37] op_sel:[1,0]
	v_mov_b32_e32 v39, v37
	v_pk_add_f32 v[36:37], v[40:41], v[38:39]
	v_pk_fma_f32 v[38:39], v[18:19], v[18:19], v[0:1] op_sel_hi:[1,1,0]
	v_mul_f32_e32 v0, v20, v20
	v_pk_add_f32 v[36:37], v[36:37], v[36:37] op_sel_hi:[0,1]
	v_pk_fma_f32 v[40:41], v[20:21], v[20:21], v[0:1] op_sel_hi:[1,1,0]
	v_mul_f32_e32 v38, v14, v14
	v_mul_f32_e32 v40, v15, v15
	v_mul_f32_e32 v36, v16, v16
	v_mul_f32_e32 v34, v17, v17
	v_pk_add_f32 v[38:39], v[38:39], v[40:41]
	v_pk_add_f32 v[34:35], v[36:37], v[34:35]
	v_pk_mul_f32 v[36:37], v[12:13], v[12:13]
	v_pk_add_f32 v[34:35], v[38:39], v[34:35]
	v_pk_mul_f32 v[38:39], v[10:11], v[10:11]
	v_mul_f32_e32 v0, v6, v6
	v_pk_mov_b32 v[40:41], v[38:39], v[36:37] op_sel:[1,0]
	v_mov_b32_e32 v39, v37
	v_pk_add_f32 v[36:37], v[40:41], v[38:39]
	v_pk_fma_f32 v[38:39], v[6:7], v[6:7], v[0:1] op_sel_hi:[1,1,0]
	v_mul_f32_e32 v0, v8, v8
	v_pk_add_f32 v[34:35], v[34:35], v[34:35] op_sel_hi:[0,1]
	v_pk_add_f32 v[36:37], v[36:37], v[36:37] op_sel_hi:[0,1]
	v_pk_fma_f32 v[40:41], v[8:9], v[8:9], v[0:1] op_sel_hi:[1,1,0]
	v_mul_f32_e32 v38, v2, v2
	v_mul_f32_e32 v40, v3, v3
	v_mul_f32_e32 v36, v4, v4
	v_mul_f32_e32 v34, v5, v5
	v_pk_add_f32 v[38:39], v[38:39], v[40:41]
	v_pk_add_f32 v[34:35], v[36:37], v[34:35]
	s_mov_b32 s2, 0x800000
	v_pk_add_f32 v[34:35], v[38:39], v[34:35]
	global_load_dwordx4 v[36:39], v[128:129], off
	global_load_dwordx4 v[84:87], v[128:129], off offset:1024
	global_load_dwordx4 v[88:91], v[128:129], off offset:2048
	global_load_dwordx4 v[92:95], v[128:129], off offset:3072
	global_load_dwordx4 v[96:99], v[132:133], off
	global_load_dwordx4 v[100:103], v[134:135], off
	global_load_dwordx4 v[104:107], v[136:137], off
	global_load_dwordx4 v[108:111], v[138:139], off
	v_add_f32_e32 v0, v34, v35
	v_and_b32_e32 v34, 64, v191
	v_add_u32_e32 v34, 64, v34
	v_xor_b32_e32 v35, 1, v191
	v_cmp_lt_i32_e32 vcc, v35, v34
	s_nop 1
	v_cndmask_b32_e32 v35, v191, v35, vcc
	v_lshlrev_b32_e32 v35, 2, v35
	ds_bpermute_b32 v35, v35, v0
	s_waitcnt lgkmcnt(0)
	v_add_f32_e32 v0, v0, v35
	v_xor_b32_e32 v35, 2, v191
	v_cmp_lt_i32_e32 vcc, v35, v34
	s_nop 1
	v_cndmask_b32_e32 v35, v191, v35, vcc
	v_lshlrev_b32_e32 v35, 2, v35
	ds_bpermute_b32 v35, v35, v0
	s_waitcnt lgkmcnt(0)
	v_add_f32_e32 v0, v0, v35
	v_xor_b32_e32 v35, 4, v191
	v_cmp_lt_i32_e32 vcc, v35, v34
	s_nop 1
	v_cndmask_b32_e32 v35, v191, v35, vcc
	v_lshlrev_b32_e32 v35, 2, v35
	ds_bpermute_b32 v35, v35, v0
	s_waitcnt lgkmcnt(0)
	v_add_f32_e32 v0, v0, v35
	v_xor_b32_e32 v35, 8, v191
	v_cmp_lt_i32_e32 vcc, v35, v34
	s_nop 1
	v_cndmask_b32_e32 v35, v191, v35, vcc
	v_lshlrev_b32_e32 v35, 2, v35
	ds_bpermute_b32 v35, v35, v0
	s_waitcnt lgkmcnt(0)
	v_add_f32_e32 v0, v0, v35
	v_xor_b32_e32 v35, 16, v191
	v_cmp_lt_i32_e32 vcc, v35, v34
	s_nop 1
	v_cndmask_b32_e32 v35, v191, v35, vcc
	v_lshlrev_b32_e32 v35, 2, v35
	ds_bpermute_b32 v35, v35, v0
	s_waitcnt lgkmcnt(0)
	v_add_f32_e32 v0, v0, v35
	v_xor_b32_e32 v35, 32, v191
	v_cmp_lt_i32_e32 vcc, v35, v34
	s_nop 1
	v_cndmask_b32_e32 v34, v191, v35, vcc
	v_lshlrev_b32_e32 v34, 2, v34
	ds_bpermute_b32 v34, v34, v0
	s_waitcnt lgkmcnt(0)
	v_add_f32_e32 v0, v0, v34
	v_fmamk_f32 v0, v0, 0x3a000000, v178
	v_cmp_gt_f32_e32 vcc, s2, v0
	v_mul_f32_e32 v34, 0x4b800000, v0
	s_nop 0
	v_cndmask_b32_e32 v0, v0, v34, vcc
	v_rsq_f32_e32 v0, v0
	s_nop 0
	v_mul_f32_e32 v34, 0x45800000, v0
	v_cndmask_b32_e32 v0, v0, v34, vcc
	v_pk_mul_f32 v[30:31], v[30:31], v[0:1] op_sel_hi:[1,0]
	v_pk_mul_f32 v[32:33], v[32:33], v[0:1] op_sel_hi:[1,0]
	s_waitcnt vmcnt(0)
	v_pk_mul_f32 v[30:31], v[36:37], v[30:31]
	v_pk_mul_f32 v[32:33], v[38:39], v[32:33]
	v_lshl_add_u64 v[34:35], v[130:131], 0, s[0:1]
	v_cvt_pk_bf16_f32 v30, v30, v31
	v_cvt_pk_bf16_f32 v31, v32, v33
	global_store_dwordx2 v[34:35], v[30:31], off
	v_pk_mul_f32 v[26:27], v[26:27], v[0:1] op_sel_hi:[1,0]
	v_pk_mul_f32 v[28:29], v[28:29], v[0:1] op_sel_hi:[1,0]
	v_pk_mul_f32 v[22:23], v[22:23], v[0:1] op_sel_hi:[1,0]
	v_pk_mul_f32 v[24:25], v[24:25], v[0:1] op_sel_hi:[1,0]
	v_pk_mul_f32 v[18:19], v[18:19], v[0:1] op_sel_hi:[1,0]
	v_pk_mul_f32 v[20:21], v[20:21], v[0:1] op_sel_hi:[1,0]
	v_pk_mul_f32 v[14:15], v[14:15], v[0:1] op_sel_hi:[1,0]
	v_pk_mul_f32 v[16:17], v[16:17], v[0:1] op_sel_hi:[1,0]
	v_pk_mul_f32 v[10:11], v[10:11], v[0:1] op_sel_hi:[1,0]
	v_pk_mul_f32 v[12:13], v[12:13], v[0:1] op_sel_hi:[1,0]
	v_pk_mul_f32 v[6:7], v[6:7], v[0:1] op_sel_hi:[1,0]
	v_pk_mul_f32 v[8:9], v[8:9], v[0:1] op_sel_hi:[1,0]
	v_pk_mul_f32 v[2:3], v[2:3], v[0:1] op_sel_hi:[1,0]
	s_mov_b64 s[0:1], 0
	v_pk_mul_f32 v[26:27], v[84:85], v[26:27]
	v_pk_mul_f32 v[28:29], v[86:87], v[28:29]
	v_cvt_pk_bf16_f32 v26, v26, v27
	v_cvt_pk_bf16_f32 v27, v28, v29
	global_store_dwordx2 v[34:35], v[26:27], off offset:512
	v_pk_mul_f32 v[22:23], v[88:89], v[22:23]
	v_pk_mul_f32 v[24:25], v[90:91], v[24:25]
	v_cvt_pk_bf16_f32 v22, v22, v23
	v_cvt_pk_bf16_f32 v23, v24, v25
	global_store_dwordx2 v[34:35], v[22:23], off offset:1024
	v_pk_mul_f32 v[18:19], v[92:93], v[18:19]
	v_pk_mul_f32 v[20:21], v[94:95], v[20:21]
	v_cvt_pk_bf16_f32 v18, v18, v19
	v_cvt_pk_bf16_f32 v19, v20, v21
	global_store_dwordx2 v[34:35], v[18:19], off offset:1536
	v_pk_mul_f32 v[14:15], v[96:97], v[14:15]
	v_pk_mul_f32 v[16:17], v[98:99], v[16:17]
	v_cvt_pk_bf16_f32 v14, v14, v15
	v_cvt_pk_bf16_f32 v15, v16, v17
	global_store_dwordx2 v[34:35], v[14:15], off offset:2048
	v_pk_mul_f32 v[10:11], v[10:11], v[100:101]
	v_pk_mul_f32 v[12:13], v[12:13], v[102:103]
	v_cvt_pk_bf16_f32 v10, v10, v11
	v_cvt_pk_bf16_f32 v11, v12, v13
	global_store_dwordx2 v[34:35], v[10:11], off offset:2560
	v_pk_mul_f32 v[6:7], v[6:7], v[104:105]
	v_pk_mul_f32 v[8:9], v[8:9], v[106:107]
	v_cvt_pk_bf16_f32 v6, v6, v7
	v_cvt_pk_bf16_f32 v7, v8, v9
	global_store_dwordx2 v[34:35], v[6:7], off offset:3072
	s_nop 1
	v_mov_b32_e32 v6, v108
	v_mov_b32_e32 v7, v109
	v_mov_b32_e32 v8, v110
	v_mov_b32_e32 v9, v111
	v_pk_mul_f32 v[2:3], v[2:3], v[6:7]
	v_mul_f32_e32 v6, v4, v0
	v_mov_b32_e32 v4, v8
	v_mov_b32_e32 v7, v0
	v_cvt_pk_bf16_f32 v2, v2, v3
	v_pk_mul_f32 v[4:5], v[4:5], v[6:7]
